# S5 pass B start: table-derived loop invariants computed after the unit loop's first wait, so tables, u rows and segment carries load in one round trip
# baseline (speedup 1.0000x reference)
; __device__ __forceinline__ int opq(int v) { asm volatile("" : "+v"(v)); return v; }
; template <bool PASS_B> __device__ __forceinline__ void ssm_tables(const Args& a, int l, int gq, int wave, SsmTab& T) {
;     ...
;     if (PASS_B) { const bf16_t* tc = (const bf16_t*)(a.ws + WS_TC) + (size_t)(l * NG + g) * GC * 128 + r * 128 + qd * 8;
; #pragma unroll
;         for (int s = 0; s < 4; ++s) T.cf[s] = *(const bf16x8*)(tc + s * 32);
;         T.dsk = a.in[I_DSK][l * 512 + g * 16 + r]; }
; __global__ void __launch_bounds__(512, 2) mk_fwd(Args a) {
;     ...
;         {   SsmTab T; ssm_tables<true>(a, l, bx & 3, wave, T); u32x4 pre[2];
;             for (int u = bx; u < NBATCH * NSEG * 4; u += G) { const int gq = u & 3, seg = (u >> 2) % NSEG, b = (u >> 2) / NSEG;
;                 const size_t r0 = (size_t)b * SEQ + (size_t)seg * (SEGB * SBLK); const int lane = opq(threadIdx.x) & 63, g = gq * 8 + wave;
;                 ssm_stage_load(a, r0, SBLK, gq, pre);
;                 float hr = 0.f, hi = 0.f;
;                 {
;                     float2 e[NSEG - 1];
; #pragma unroll
;                     for (int i = 0; i < NSEG - 1; ++i) e[i] = (i < seg) ? *(const float2*)(Ebuf + ((((size_t)b * NSEG + i) * NG + g) * NP + lane) * 2) : make_float2(0.f, 0.f);
.LBB0_437:
	s_or_b64 exec, exec, s[0:1]
	v_readlane_b32 s0, v253, 42
	v_lshrrev_b32_e32 v0, 1, v21
	s_add_u32 s0, s0, s6
	v_readlane_b32 s1, v253, 43
	v_readlane_b32 s22, v255, 41
	s_addc_u32 s1, s1, s7
	s_lshl_b32 s24, s22, 9
	v_readlane_b32 s4, v253, 45
	v_and_b32_e32 v21, 24, v0
	v_lshlrev_b32_e32 v0, 8, v20
	s_add_i32 s6, s24, s4
	v_lshl_add_u64 v[2:3], s[0:1], 0, v[0:1]
	v_lshlrev_b32_e32 v0, 1, v21
	v_lshl_add_u64 v[2:3], v[2:3], 0, v[0:1]
	v_or_b32_e32 v0, s6, v20
	v_readlane_b32 s4, v252, 16
	global_load_dwordx4 v[60:63], v[2:3], off
	global_load_dwordx4 v[64:67], v[2:3], off offset:64
	global_load_dwordx4 v[68:71], v[2:3], off offset:128
	global_load_dwordx4 v[72:75], v[2:3], off offset:192
	v_readlane_b32 s10, v252, 22
	v_readlane_b32 s11, v252, 23
	v_readlane_b32 s0, v255, 39
	v_readlane_b32 s1, v255, 40
	v_lshl_add_u64 v[2:3], v[0:1], 2, s[10:11]
	global_load_dword v90, v[2:3], off
	v_readlane_b32 s23, v255, 42
	s_and_b64 vcc, exec, s[0:1]
	s_nop 0
	v_readlane_b32 s5, v252, 17
	v_readlane_b32 s6, v252, 18
	v_readlane_b32 s7, v252, 19
	v_readlane_b32 s8, v252, 20
	v_readlane_b32 s9, v252, 21
	v_readlane_b32 s12, v252, 24
	v_readlane_b32 s13, v252, 25
	v_readlane_b32 s14, v252, 26
	v_readlane_b32 s15, v252, 27
	v_readlane_b32 s16, v252, 28
	v_readlane_b32 s17, v252, 29
	v_readlane_b32 s18, v252, 30
	v_readlane_b32 s19, v252, 31
	s_cbranch_vccnz .LBB0_477
	s_lshl_b64 s[0:1], s[22:23], 16
	s_add_u32 s22, s68, s0
	s_addc_u32 s23, s69, s1
	s_mov_b32 s25, s2
	s_mov_b32 s28, s2

; template <bool PASS_B> __device__ __forceinline__ void ssm_unit(const Args& a, LAS unsigned char* lds, const SsmTab& T, const u32x4 (&pre)[2], int l, size_t row0, int ntok, int gq, float& hr_io, float& hi_io, int wave) {
;     ...
;             f32x2 h = {hr, hi}; const f32x2 a1 = {ar, ar}, a2 = {-ai, ai};
; __global__ void __launch_bounds__(512, 2) mk_fwd(Args a) {
;     ...
;                     float2 e[NSEG - 1];
; #pragma unroll
;                     for (int i = 0; i < NSEG - 1; ++i) e[i] = (i < seg) ? *(const float2*)(Ebuf + ((((size_t)b * NSEG + i) * NG + g) * NP + lane) * 2) : make_float2(0.f, 0.f);
; #pragma unroll
;                     for (int i = 0; i < NSEG - 1; ++i) if (i < seg) { const float nr = T.ta[2] * hr - T.ta[3] * hi + e[i].x, ni = T.ta[2] * hi + T.ta[3] * hr + e[i].y; hr = nr; hi = ni; } }
.LBB0_457:
	s_waitcnt vmcnt(0)
	v_xor_b32_e32 v2, 0x80000000, v77
	v_mul_f32_e32 v91, 0, v79
	v_mov_b32_e32 v80, v76
	v_mov_b32_e32 v81, v76
	v_mov_b32_e32 v3, v77
	v_fma_f32 v92, v78, 0, -v91
	v_fmac_f32_e32 v91, 0, v78
	v_add_f32_e32 v0, v92, v22
	v_add_f32_e32 v22, v91, v23
	v_cndmask_b32_e64 v22, 0, v22, s[6:7]
	v_cndmask_b32_e64 v0, 0, v0, s[6:7]
	v_mul_f32_e32 v23, v79, v0
	v_mul_f32_e32 v24, v79, v22
	v_fmac_f32_e32 v23, v78, v22
	v_fma_f32 v24, v78, v0, -v24
	v_add_f32_e32 v20, v24, v20
	v_add_f32_e32 v21, v23, v21
	v_cndmask_b32_e64 v21, v22, v21, s[8:9]
	v_cndmask_b32_e64 v0, v0, v20, s[8:9]
	v_mul_f32_e32 v20, v79, v0
	v_mul_f32_e32 v22, v79, v21
	v_fmac_f32_e32 v20, v78, v21
	v_fma_f32 v22, v78, v0, -v22
	v_add_f32_e32 v22, v22, v82
	v_add_f32_e32 v20, v20, v83
	v_cndmask_b32_e64 v20, v21, v20, s[10:11]
	v_cndmask_b32_e64 v0, v0, v22, s[10:11]
	v_mul_f32_e32 v21, v79, v0
	v_mul_f32_e32 v22, v79, v20
	v_fmac_f32_e32 v21, v78, v20
	v_fma_f32 v22, v78, v0, -v22
	v_add_f32_e32 v22, v22, v26
	v_add_f32_e32 v21, v21, v27
	v_cndmask_b32_e64 v20, v20, v21, s[12:13]
	v_cndmask_b32_e64 v0, v0, v22, s[12:13]
	v_mul_f32_e32 v21, v79, v0
	v_mul_f32_e32 v22, v79, v20
	v_fmac_f32_e32 v21, v78, v20
	v_fma_f32 v22, v78, v0, -v22
	v_add_f32_e32 v22, v22, v86
	v_add_f32_e32 v21, v21, v87
	s_and_b32 s26, s25, 3
	v_cndmask_b32_e64 v20, v20, v21, s[14:15]
	v_cndmask_b32_e64 v0, v0, v22, s[14:15]
	s_lshl_b32 s26, s26, 7
	v_readlane_b32 s4, v253, 46
	v_mul_f32_e32 v21, v79, v0
	v_mul_f32_e32 v22, v79, v20
	s_add_i32 s26, s4, s26
	v_fmac_f32_e32 v21, v78, v20
	v_fma_f32 v22, v78, v0, -v22
	s_lshl_b32 s26, s26, 1
	v_add_f32_e32 v22, v22, v84
	v_add_f32_e32 v21, v21, v85
	s_lshl_b64 s[6:7], s[66:67], 21
	s_lshl_b64 s[8:9], s[72:73], 18
	v_cndmask_b32_e64 v20, v20, v21, s[16:17]
	v_cndmask_b32_e64 v0, v0, v22, s[16:17]
	s_add_u32 s6, s6, s8
	v_mul_f32_e32 v21, v79, v0
	v_mul_f32_e32 v22, v79, v20
	s_addc_u32 s7, s7, s9
	v_fmac_f32_e32 v21, v78, v20
	v_fma_f32 v22, v78, v0, -v22
	s_add_u32 s6, s6, s26
	v_add_f32_e32 v22, v22, v88
	v_add_f32_e32 v21, v21, v89
	s_addc_u32 s7, s7, 0
	v_readlane_b32 s4, v255, 12
	v_cndmask_b32_e64 v83, v20, v21, s[18:19]
	v_cndmask_b32_e64 v82, v0, v22, s[18:19]
	s_add_u32 s6, s4, s6
	v_readlane_b32 s4, v255, 13
	v_mov_b64_e32 v[26:27], v[18:19]
	s_addc_u32 s7, s4, s7
	s_mov_b32 s12, 0
	v_mov_b64_e32 v[24:25], v[16:17]
	v_mov_b64_e32 v[22:23], v[14:15]
	v_mov_b64_e32 v[20:21], v[12:13]
	s_mov_b32 s8, s12
	s_add_i32 s12, s12, 1
	s_cmp_eq_u32 s8, 3
	s_cbranch_scc1 .LBB0_464
	s_branch .LBB0_459

; __device__ __forceinline__ int opq(int v) { asm volatile("" : "+v"(v)); return v; }
; template <bool PASS_B> __device__ __forceinline__ void ssm_unit(const Args& a, LAS unsigned char* lds, const SsmTab& T, const u32x4 (&pre)[2], int l, size_t row0, int ntok, int gq, float& hr_io, float& hi_io, int wave) {
;     ...
;             f32x2 h = {hr, hi}; const f32x2 a1 = {ar, ar}, a2 = {-ai, ai};
; __global__ void __launch_bounds__(512, 2) mk_fwd(Args a) {
;     ...
;             for (int v = bx; v < DEC_B * 4; v += G) { const int gq = v & 3, b = v >> 2; const int lane = opq(threadIdx.x) & 63, g = gq * 8 + wave;
;                 const size_t so = ((size_t)l * DEC_B + b) * NG * NP + g * NP + lane;
;                 ssm_stage_load(a, (size_t)NTOK_P + b * DEC_T, DEC_T, gq, pre);
;                 float hr = a.in[I_SR][so], hi = a.in[I_SI][so];
;                 ssm_unit<true>(a, lds, T, pre, l, (size_t)NTOK_P + b * DEC_T, DEC_T, gq, hr, hi, wave);
.LBB0_477:
	s_waitcnt vmcnt(0)
	v_xor_b32_e32 v2, 0x80000000, v77
	v_mov_b64_e32 v[26:27], v[18:19]
	v_mov_b64_e32 v[24:25], v[16:17]
	v_mov_b64_e32 v[22:23], v[14:15]
	v_mov_b64_e32 v[20:21], v[12:13]
	s_branch .LBB0_479
